# 64-byte alignment of the five GEMM K-loop heads (P1 P2 P7 P9 P10); prio 1 moved to waves 4-7 in P6
# speedup vs baseline: 1.0556x; 1.0024x over previous
.LBB0_90:
	s_ashr_i32 s95, s94, 31
	s_lshl_b64 s[4:5], s[94:95], 19
	s_add_u32 s96, s90, s4
	s_addc_u32 s97, s91, s5
	s_and_b64 s[4:5], s[0:1], exec
	s_cselect_b32 s29, s97, s53
	s_cselect_b32 s30, s96, s52
	s_ashr_i32 s93, s92, 31
	s_lshl_b64 s[4:5], s[92:93], 19
	s_add_u32 s4, s6, s4
	s_addc_u32 s5, s7, s5
	s_and_b64 s[56:57], s[0:1], exec
	s_cselect_b32 s31, s5, s55
	s_cselect_b32 s35, s4, s54
	s_add_u32 s52, s52, 0x40080
	s_addc_u32 s53, s53, 0
	s_add_u32 s58, s54, 0x100
	v_mov_b32_e32 v2, 0
	s_addc_u32 s59, s55, 0
	s_mov_b32 s60, -2
	v_mov_b32_e32 v3, v2
	v_mov_b32_e32 v4, v2
	v_mov_b32_e32 v5, v2
	v_mov_b32_e32 v6, v2
	v_mov_b32_e32 v7, v2
	v_mov_b32_e32 v8, v2
	v_mov_b32_e32 v9, v2
	v_mov_b32_e32 v18, v2
	v_mov_b32_e32 v19, v2
	v_mov_b32_e32 v20, v2
	v_mov_b32_e32 v21, v2
	v_mov_b32_e32 v22, v2
	v_mov_b32_e32 v23, v2
	v_mov_b32_e32 v24, v2
	v_mov_b32_e32 v25, v2
	v_mov_b32_e32 v34, v2
	v_mov_b32_e32 v35, v2
	v_mov_b32_e32 v36, v2
	v_mov_b32_e32 v37, v2
	v_mov_b32_e32 v38, v2
	v_mov_b32_e32 v39, v2
	v_mov_b32_e32 v40, v2
	v_mov_b32_e32 v41, v2
	v_mov_b32_e32 v50, v2
	v_mov_b32_e32 v51, v2
	v_mov_b32_e32 v52, v2
	v_mov_b32_e32 v53, v2
	v_mov_b32_e32 v54, v2
	v_mov_b32_e32 v55, v2
	v_mov_b32_e32 v56, v2
	v_mov_b32_e32 v57, v2
	v_mov_b32_e32 v10, v2
	v_mov_b32_e32 v11, v2
	v_mov_b32_e32 v12, v2
	v_mov_b32_e32 v13, v2
	v_mov_b32_e32 v14, v2
	v_mov_b32_e32 v15, v2
	v_mov_b32_e32 v16, v2
	v_mov_b32_e32 v17, v2
	v_mov_b32_e32 v26, v2
	v_mov_b32_e32 v27, v2
	v_mov_b32_e32 v28, v2
	v_mov_b32_e32 v29, v2
	v_mov_b32_e32 v30, v2
	v_mov_b32_e32 v31, v2
	v_mov_b32_e32 v32, v2
	v_mov_b32_e32 v33, v2
	v_mov_b32_e32 v42, v2
	v_mov_b32_e32 v43, v2
	v_mov_b32_e32 v44, v2
	v_mov_b32_e32 v45, v2
	v_mov_b32_e32 v46, v2
	v_mov_b32_e32 v47, v2
	v_mov_b32_e32 v48, v2
	v_mov_b32_e32 v49, v2
	v_mov_b32_e32 v58, v2
	v_mov_b32_e32 v59, v2
	v_mov_b32_e32 v60, v2
	v_mov_b32_e32 v61, v2
	v_mov_b32_e32 v62, v2
	v_mov_b32_e32 v63, v2
	v_mov_b32_e32 v64, v2
	v_mov_b32_e32 v65, v2
	v_mov_b32_e32 v66, v2
	v_mov_b32_e32 v67, v2
	v_mov_b32_e32 v68, v2
	v_mov_b32_e32 v69, v2
	v_mov_b32_e32 v70, v2
	v_mov_b32_e32 v71, v2
	v_mov_b32_e32 v72, v2
	v_mov_b32_e32 v73, v2
	v_mov_b32_e32 v82, v2
	v_mov_b32_e32 v83, v2
	v_mov_b32_e32 v84, v2
	v_mov_b32_e32 v85, v2
	v_mov_b32_e32 v86, v2
	v_mov_b32_e32 v87, v2
	v_mov_b32_e32 v88, v2
	v_mov_b32_e32 v89, v2
	v_mov_b32_e32 v98, v2
	v_mov_b32_e32 v99, v2
	v_mov_b32_e32 v100, v2
	v_mov_b32_e32 v101, v2
	v_mov_b32_e32 v102, v2
	v_mov_b32_e32 v103, v2
	v_mov_b32_e32 v104, v2
	v_mov_b32_e32 v105, v2
	v_mov_b32_e32 v114, v2
	v_mov_b32_e32 v115, v2
	v_mov_b32_e32 v116, v2
	v_mov_b32_e32 v117, v2
	v_mov_b32_e32 v118, v2
	v_mov_b32_e32 v119, v2
	v_mov_b32_e32 v120, v2
	v_mov_b32_e32 v121, v2
	v_mov_b32_e32 v74, v2
	v_mov_b32_e32 v75, v2
	v_mov_b32_e32 v76, v2
	v_mov_b32_e32 v77, v2
	v_mov_b32_e32 v78, v2
	v_mov_b32_e32 v79, v2
	v_mov_b32_e32 v80, v2
	v_mov_b32_e32 v81, v2
	v_mov_b32_e32 v90, v2
	v_mov_b32_e32 v91, v2
	v_mov_b32_e32 v92, v2
	v_mov_b32_e32 v93, v2
	v_mov_b32_e32 v94, v2
	v_mov_b32_e32 v95, v2
	v_mov_b32_e32 v96, v2
	v_mov_b32_e32 v97, v2
	v_mov_b32_e32 v106, v2
	v_mov_b32_e32 v107, v2
	v_mov_b32_e32 v108, v2
	v_mov_b32_e32 v109, v2
	v_mov_b32_e32 v110, v2
	v_mov_b32_e32 v111, v2
	v_mov_b32_e32 v112, v2
	v_mov_b32_e32 v113, v2
	v_mov_b32_e32 v122, v2
	v_mov_b32_e32 v123, v2
	v_mov_b32_e32 v124, v2
	v_mov_b32_e32 v125, v2
	v_mov_b32_e32 v126, v2
	v_mov_b32_e32 v127, v2
	v_mov_b32_e32 v128, v2
	v_mov_b32_e32 v129, v2
	.p2align	6

.LBB0_231:
	s_add_i32 s21, s13, -2
	s_add_u32 s66, s52, 0x100
	v_mov_b32_e32 v2, 0
	s_addc_u32 s67, s53, 0
	s_mov_b32 s54, 0
	v_mov_b32_e32 v3, v2
	v_mov_b32_e32 v4, v2
	v_mov_b32_e32 v5, v2
	v_mov_b32_e32 v6, v2
	v_mov_b32_e32 v7, v2
	v_mov_b32_e32 v8, v2
	v_mov_b32_e32 v9, v2
	v_mov_b32_e32 v10, v2
	v_mov_b32_e32 v11, v2
	v_mov_b32_e32 v12, v2
	v_mov_b32_e32 v13, v2
	v_mov_b32_e32 v14, v2
	v_mov_b32_e32 v15, v2
	v_mov_b32_e32 v16, v2
	v_mov_b32_e32 v17, v2
	v_mov_b32_e32 v26, v2
	v_mov_b32_e32 v27, v2
	v_mov_b32_e32 v28, v2
	v_mov_b32_e32 v29, v2
	v_mov_b32_e32 v30, v2
	v_mov_b32_e32 v31, v2
	v_mov_b32_e32 v32, v2
	v_mov_b32_e32 v33, v2
	v_mov_b32_e32 v42, v2
	v_mov_b32_e32 v43, v2
	v_mov_b32_e32 v44, v2
	v_mov_b32_e32 v45, v2
	v_mov_b32_e32 v46, v2
	v_mov_b32_e32 v47, v2
	v_mov_b32_e32 v48, v2
	v_mov_b32_e32 v49, v2
	v_mov_b32_e32 v18, v2
	v_mov_b32_e32 v19, v2
	v_mov_b32_e32 v20, v2
	v_mov_b32_e32 v21, v2
	v_mov_b32_e32 v22, v2
	v_mov_b32_e32 v23, v2
	v_mov_b32_e32 v24, v2
	v_mov_b32_e32 v25, v2
	v_mov_b32_e32 v34, v2
	v_mov_b32_e32 v35, v2
	v_mov_b32_e32 v36, v2
	v_mov_b32_e32 v37, v2
	v_mov_b32_e32 v38, v2
	v_mov_b32_e32 v39, v2
	v_mov_b32_e32 v40, v2
	v_mov_b32_e32 v41, v2
	v_mov_b32_e32 v50, v2
	v_mov_b32_e32 v51, v2
	v_mov_b32_e32 v52, v2
	v_mov_b32_e32 v53, v2
	v_mov_b32_e32 v54, v2
	v_mov_b32_e32 v55, v2
	v_mov_b32_e32 v56, v2
	v_mov_b32_e32 v57, v2
	v_mov_b32_e32 v58, v2
	v_mov_b32_e32 v59, v2
	v_mov_b32_e32 v60, v2
	v_mov_b32_e32 v61, v2
	v_mov_b32_e32 v62, v2
	v_mov_b32_e32 v63, v2
	v_mov_b32_e32 v64, v2
	v_mov_b32_e32 v65, v2
	v_mov_b32_e32 v66, v2
	v_mov_b32_e32 v67, v2
	v_mov_b32_e32 v68, v2
	v_mov_b32_e32 v69, v2
	v_mov_b32_e32 v70, v2
	v_mov_b32_e32 v71, v2
	v_mov_b32_e32 v72, v2
	v_mov_b32_e32 v73, v2
	v_mov_b32_e32 v74, v2
	v_mov_b32_e32 v75, v2
	v_mov_b32_e32 v76, v2
	v_mov_b32_e32 v77, v2
	v_mov_b32_e32 v78, v2
	v_mov_b32_e32 v79, v2
	v_mov_b32_e32 v80, v2
	v_mov_b32_e32 v81, v2
	v_mov_b32_e32 v90, v2
	v_mov_b32_e32 v91, v2
	v_mov_b32_e32 v92, v2
	v_mov_b32_e32 v93, v2
	v_mov_b32_e32 v94, v2
	v_mov_b32_e32 v95, v2
	v_mov_b32_e32 v96, v2
	v_mov_b32_e32 v97, v2
	v_mov_b32_e32 v106, v2
	v_mov_b32_e32 v107, v2
	v_mov_b32_e32 v108, v2
	v_mov_b32_e32 v109, v2
	v_mov_b32_e32 v110, v2
	v_mov_b32_e32 v111, v2
	v_mov_b32_e32 v112, v2
	v_mov_b32_e32 v113, v2
	v_mov_b32_e32 v82, v2
	v_mov_b32_e32 v83, v2
	v_mov_b32_e32 v84, v2
	v_mov_b32_e32 v85, v2
	v_mov_b32_e32 v86, v2
	v_mov_b32_e32 v87, v2
	v_mov_b32_e32 v88, v2
	v_mov_b32_e32 v89, v2
	v_mov_b32_e32 v98, v2
	v_mov_b32_e32 v99, v2
	v_mov_b32_e32 v100, v2
	v_mov_b32_e32 v101, v2
	v_mov_b32_e32 v102, v2
	v_mov_b32_e32 v103, v2
	v_mov_b32_e32 v104, v2
	v_mov_b32_e32 v105, v2
	v_mov_b32_e32 v114, v2
	v_mov_b32_e32 v115, v2
	v_mov_b32_e32 v116, v2
	v_mov_b32_e32 v117, v2
	v_mov_b32_e32 v118, v2
	v_mov_b32_e32 v119, v2
	v_mov_b32_e32 v120, v2
	v_mov_b32_e32 v121, v2
	v_mov_b32_e32 v122, v2
	v_mov_b32_e32 v123, v2
	v_mov_b32_e32 v124, v2
	v_mov_b32_e32 v125, v2
	v_mov_b32_e32 v126, v2
	v_mov_b32_e32 v127, v2
	v_mov_b32_e32 v128, v2
	v_mov_b32_e32 v129, v2
	.p2align	6

.LBB0_1297:
.LBB0_1298:
	s_cmp_lt_i32 s14, 7
	s_cselect_b64 s[0:1], -1, 0
	s_cmp_gt_i32 s15, 6
	s_cselect_b64 s[4:5], -1, 0
	s_and_b64 s[0:1], s[0:1], s[4:5]
	s_andn2_b64 vcc, exec, s[0:1]
	s_cbranch_vccnz .LBB0_1473
	v_readfirstlane_b32 s62, v0
	s_nop 3
	s_lshr_b32 s62, s62, 8
	s_cmp_eq_u32 s62, 1
	s_cbranch_scc0 .Lp6_noprio
	s_setprio 1

.LBB0_1503:
	s_add_i32 s13, s12, -2
	s_add_u32 s42, s42, 0x40080
	s_addc_u32 s43, s43, 0
	s_add_u32 s25, s44, 0x100
	v_mov_b32_e32 v2, 0
	s_addc_u32 s37, s45, 0
	s_mov_b32 s39, 0
	v_mov_b32_e32 v3, v2
	v_mov_b32_e32 v4, v2
	v_mov_b32_e32 v5, v2
	v_mov_b32_e32 v6, v2
	v_mov_b32_e32 v7, v2
	v_mov_b32_e32 v8, v2
	v_mov_b32_e32 v9, v2
	v_mov_b32_e32 v10, v2
	v_mov_b32_e32 v11, v2
	v_mov_b32_e32 v12, v2
	v_mov_b32_e32 v13, v2
	v_mov_b32_e32 v14, v2
	v_mov_b32_e32 v15, v2
	v_mov_b32_e32 v16, v2
	v_mov_b32_e32 v17, v2
	v_mov_b32_e32 v26, v2
	v_mov_b32_e32 v27, v2
	v_mov_b32_e32 v28, v2
	v_mov_b32_e32 v29, v2
	v_mov_b32_e32 v30, v2
	v_mov_b32_e32 v31, v2
	v_mov_b32_e32 v32, v2
	v_mov_b32_e32 v33, v2
	v_mov_b32_e32 v42, v2
	v_mov_b32_e32 v43, v2
	v_mov_b32_e32 v44, v2
	v_mov_b32_e32 v45, v2
	v_mov_b32_e32 v46, v2
	v_mov_b32_e32 v47, v2
	v_mov_b32_e32 v48, v2
	v_mov_b32_e32 v49, v2
	v_mov_b32_e32 v18, v2
	v_mov_b32_e32 v19, v2
	v_mov_b32_e32 v20, v2
	v_mov_b32_e32 v21, v2
	v_mov_b32_e32 v22, v2
	v_mov_b32_e32 v23, v2
	v_mov_b32_e32 v24, v2
	v_mov_b32_e32 v25, v2
	v_mov_b32_e32 v34, v2
	v_mov_b32_e32 v35, v2
	v_mov_b32_e32 v36, v2
	v_mov_b32_e32 v37, v2
	v_mov_b32_e32 v38, v2
	v_mov_b32_e32 v39, v2
	v_mov_b32_e32 v40, v2
	v_mov_b32_e32 v41, v2
	v_mov_b32_e32 v50, v2
	v_mov_b32_e32 v51, v2
	v_mov_b32_e32 v52, v2
	v_mov_b32_e32 v53, v2
	v_mov_b32_e32 v54, v2
	v_mov_b32_e32 v55, v2
	v_mov_b32_e32 v56, v2
	v_mov_b32_e32 v57, v2
	v_mov_b32_e32 v58, v2
	v_mov_b32_e32 v59, v2
	v_mov_b32_e32 v60, v2
	v_mov_b32_e32 v61, v2
	v_mov_b32_e32 v62, v2
	v_mov_b32_e32 v63, v2
	v_mov_b32_e32 v64, v2
	v_mov_b32_e32 v65, v2
	v_mov_b32_e32 v66, v2
	v_mov_b32_e32 v67, v2
	v_mov_b32_e32 v68, v2
	v_mov_b32_e32 v69, v2
	v_mov_b32_e32 v70, v2
	v_mov_b32_e32 v71, v2
	v_mov_b32_e32 v72, v2
	v_mov_b32_e32 v73, v2
	v_mov_b32_e32 v74, v2
	v_mov_b32_e32 v75, v2
	v_mov_b32_e32 v76, v2
	v_mov_b32_e32 v77, v2
	v_mov_b32_e32 v78, v2
	v_mov_b32_e32 v79, v2
	v_mov_b32_e32 v80, v2
	v_mov_b32_e32 v81, v2
	v_mov_b32_e32 v90, v2
	v_mov_b32_e32 v91, v2
	v_mov_b32_e32 v92, v2
	v_mov_b32_e32 v93, v2
	v_mov_b32_e32 v94, v2
	v_mov_b32_e32 v95, v2
	v_mov_b32_e32 v96, v2
	v_mov_b32_e32 v97, v2
	v_mov_b32_e32 v106, v2
	v_mov_b32_e32 v107, v2
	v_mov_b32_e32 v108, v2
	v_mov_b32_e32 v109, v2
	v_mov_b32_e32 v110, v2
	v_mov_b32_e32 v111, v2
	v_mov_b32_e32 v112, v2
	v_mov_b32_e32 v113, v2
	v_mov_b32_e32 v82, v2
	v_mov_b32_e32 v83, v2
	v_mov_b32_e32 v84, v2
	v_mov_b32_e32 v85, v2
	v_mov_b32_e32 v86, v2
	v_mov_b32_e32 v87, v2
	v_mov_b32_e32 v88, v2
	v_mov_b32_e32 v89, v2
	v_mov_b32_e32 v98, v2
	v_mov_b32_e32 v99, v2
	v_mov_b32_e32 v100, v2
	v_mov_b32_e32 v101, v2
	v_mov_b32_e32 v102, v2
	v_mov_b32_e32 v103, v2
	v_mov_b32_e32 v104, v2
	v_mov_b32_e32 v105, v2
	v_mov_b32_e32 v114, v2
	v_mov_b32_e32 v115, v2
	v_mov_b32_e32 v116, v2
	v_mov_b32_e32 v117, v2
	v_mov_b32_e32 v118, v2
	v_mov_b32_e32 v119, v2
	v_mov_b32_e32 v120, v2
	v_mov_b32_e32 v121, v2
	v_mov_b32_e32 v122, v2
	v_mov_b32_e32 v123, v2
	v_mov_b32_e32 v124, v2
	v_mov_b32_e32 v125, v2
	v_mov_b32_e32 v126, v2
	v_mov_b32_e32 v127, v2
	v_mov_b32_e32 v128, v2
	v_mov_b32_e32 v129, v2
	.p2align	6

.LBB0_1662:
	s_ashr_i32 s21, s20, 31
	s_lshl_b64 s[12:13], s[20:21], 19
	s_add_u32 s22, s90, s12
	s_addc_u32 s23, s91, s13
	s_and_b64 s[12:13], s[0:1], exec
	s_cselect_b32 s12, s23, s29
	s_cselect_b32 s13, s22, s28
	s_ashr_i32 s11, s10, 31
	s_lshl_b64 s[24:25], s[10:11], 19
	s_add_u32 s24, s30, s24
	s_addc_u32 s25, s31, s25
	s_and_b64 s[36:37], s[0:1], exec
	s_cselect_b32 s11, s25, s35
	s_cselect_b32 s21, s24, s34
	s_add_u32 s28, s28, 0x40080
	s_addc_u32 s29, s29, 0
	s_add_u32 s50, s34, 0x100
	v_mov_b32_e32 v2, 0
	s_addc_u32 s51, s35, 0
	s_mov_b32 s52, -2
	v_mov_b32_e32 v3, v2
	v_mov_b32_e32 v4, v2
	v_mov_b32_e32 v5, v2
	v_mov_b32_e32 v6, v2
	v_mov_b32_e32 v7, v2
	v_mov_b32_e32 v8, v2
	v_mov_b32_e32 v9, v2
	v_mov_b32_e32 v18, v2
	v_mov_b32_e32 v19, v2
	v_mov_b32_e32 v20, v2
	v_mov_b32_e32 v21, v2
	v_mov_b32_e32 v22, v2
	v_mov_b32_e32 v23, v2
	v_mov_b32_e32 v24, v2
	v_mov_b32_e32 v25, v2
	v_mov_b32_e32 v34, v2
	v_mov_b32_e32 v35, v2
	v_mov_b32_e32 v36, v2
	v_mov_b32_e32 v37, v2
	v_mov_b32_e32 v38, v2
	v_mov_b32_e32 v39, v2
	v_mov_b32_e32 v40, v2
	v_mov_b32_e32 v41, v2
	v_mov_b32_e32 v50, v2
	v_mov_b32_e32 v51, v2
	v_mov_b32_e32 v52, v2
	v_mov_b32_e32 v53, v2
	v_mov_b32_e32 v54, v2
	v_mov_b32_e32 v55, v2
	v_mov_b32_e32 v56, v2
	v_mov_b32_e32 v57, v2
	v_mov_b32_e32 v10, v2
	v_mov_b32_e32 v11, v2
	v_mov_b32_e32 v12, v2
	v_mov_b32_e32 v13, v2
	v_mov_b32_e32 v14, v2
	v_mov_b32_e32 v15, v2
	v_mov_b32_e32 v16, v2
	v_mov_b32_e32 v17, v2
	v_mov_b32_e32 v26, v2
	v_mov_b32_e32 v27, v2
	v_mov_b32_e32 v28, v2
	v_mov_b32_e32 v29, v2
	v_mov_b32_e32 v30, v2
	v_mov_b32_e32 v31, v2
	v_mov_b32_e32 v32, v2
	v_mov_b32_e32 v33, v2
	v_mov_b32_e32 v42, v2
	v_mov_b32_e32 v43, v2
	v_mov_b32_e32 v44, v2
	v_mov_b32_e32 v45, v2
	v_mov_b32_e32 v46, v2
	v_mov_b32_e32 v47, v2
	v_mov_b32_e32 v48, v2
	v_mov_b32_e32 v49, v2
	v_mov_b32_e32 v58, v2
	v_mov_b32_e32 v59, v2
	v_mov_b32_e32 v60, v2
	v_mov_b32_e32 v61, v2
	v_mov_b32_e32 v62, v2
	v_mov_b32_e32 v63, v2
	v_mov_b32_e32 v64, v2
	v_mov_b32_e32 v65, v2
	v_mov_b32_e32 v66, v2
	v_mov_b32_e32 v67, v2
	v_mov_b32_e32 v68, v2
	v_mov_b32_e32 v69, v2
	v_mov_b32_e32 v70, v2
	v_mov_b32_e32 v71, v2
	v_mov_b32_e32 v72, v2
	v_mov_b32_e32 v73, v2
	v_mov_b32_e32 v82, v2
	v_mov_b32_e32 v83, v2
	v_mov_b32_e32 v84, v2
	v_mov_b32_e32 v85, v2
	v_mov_b32_e32 v86, v2
	v_mov_b32_e32 v87, v2
	v_mov_b32_e32 v88, v2
	v_mov_b32_e32 v89, v2
	v_mov_b32_e32 v98, v2
	v_mov_b32_e32 v99, v2
	v_mov_b32_e32 v100, v2
	v_mov_b32_e32 v101, v2
	v_mov_b32_e32 v102, v2
	v_mov_b32_e32 v103, v2
	v_mov_b32_e32 v104, v2
	v_mov_b32_e32 v105, v2
	v_mov_b32_e32 v114, v2
	v_mov_b32_e32 v115, v2
	v_mov_b32_e32 v116, v2
	v_mov_b32_e32 v117, v2
	v_mov_b32_e32 v118, v2
	v_mov_b32_e32 v119, v2
	v_mov_b32_e32 v120, v2
	v_mov_b32_e32 v121, v2
	v_mov_b32_e32 v74, v2
	v_mov_b32_e32 v75, v2
	v_mov_b32_e32 v76, v2
	v_mov_b32_e32 v77, v2
	v_mov_b32_e32 v78, v2
	v_mov_b32_e32 v79, v2
	v_mov_b32_e32 v80, v2
	v_mov_b32_e32 v81, v2
	v_mov_b32_e32 v90, v2
	v_mov_b32_e32 v91, v2
	v_mov_b32_e32 v92, v2
	v_mov_b32_e32 v93, v2
	v_mov_b32_e32 v94, v2
	v_mov_b32_e32 v95, v2
	v_mov_b32_e32 v96, v2
	v_mov_b32_e32 v97, v2
	v_mov_b32_e32 v106, v2
	v_mov_b32_e32 v107, v2
	v_mov_b32_e32 v108, v2
	v_mov_b32_e32 v109, v2
	v_mov_b32_e32 v110, v2
	v_mov_b32_e32 v111, v2
	v_mov_b32_e32 v112, v2
	v_mov_b32_e32 v113, v2
	v_mov_b32_e32 v122, v2
	v_mov_b32_e32 v123, v2
	v_mov_b32_e32 v124, v2
	v_mov_b32_e32 v125, v2
	v_mov_b32_e32 v126, v2
	v_mov_b32_e32 v127, v2
	v_mov_b32_e32 v128, v2
	v_mov_b32_e32 v129, v2
	.p2align	6

.LBB0_1755:
	s_add_i32 s19, s13, -2
	s_add_u32 s59, s26, 0x100
	v_mov_b32_e32 v2, 0
	s_addc_u32 s60, s27, 0
	s_mov_b32 s28, 0
	v_mov_b32_e32 v3, v2
	v_mov_b32_e32 v4, v2
	v_mov_b32_e32 v5, v2
	v_mov_b32_e32 v6, v2
	v_mov_b32_e32 v7, v2
	v_mov_b32_e32 v8, v2
	v_mov_b32_e32 v9, v2
	v_mov_b32_e32 v10, v2
	v_mov_b32_e32 v11, v2
	v_mov_b32_e32 v12, v2
	v_mov_b32_e32 v13, v2
	v_mov_b32_e32 v14, v2
	v_mov_b32_e32 v15, v2
	v_mov_b32_e32 v16, v2
	v_mov_b32_e32 v17, v2
	v_mov_b32_e32 v26, v2
	v_mov_b32_e32 v27, v2
	v_mov_b32_e32 v28, v2
	v_mov_b32_e32 v29, v2
	v_mov_b32_e32 v30, v2
	v_mov_b32_e32 v31, v2
	v_mov_b32_e32 v32, v2
	v_mov_b32_e32 v33, v2
	v_mov_b32_e32 v42, v2
	v_mov_b32_e32 v43, v2
	v_mov_b32_e32 v44, v2
	v_mov_b32_e32 v45, v2
	v_mov_b32_e32 v46, v2
	v_mov_b32_e32 v47, v2
	v_mov_b32_e32 v48, v2
	v_mov_b32_e32 v49, v2
	v_mov_b32_e32 v18, v2
	v_mov_b32_e32 v19, v2
	v_mov_b32_e32 v20, v2
	v_mov_b32_e32 v21, v2
	v_mov_b32_e32 v22, v2
	v_mov_b32_e32 v23, v2
	v_mov_b32_e32 v24, v2
	v_mov_b32_e32 v25, v2
	v_mov_b32_e32 v34, v2
	v_mov_b32_e32 v35, v2
	v_mov_b32_e32 v36, v2
	v_mov_b32_e32 v37, v2
	v_mov_b32_e32 v38, v2
	v_mov_b32_e32 v39, v2
	v_mov_b32_e32 v40, v2
	v_mov_b32_e32 v41, v2
	v_mov_b32_e32 v50, v2
	v_mov_b32_e32 v51, v2
	v_mov_b32_e32 v52, v2
	v_mov_b32_e32 v53, v2
	v_mov_b32_e32 v54, v2
	v_mov_b32_e32 v55, v2
	v_mov_b32_e32 v56, v2
	v_mov_b32_e32 v57, v2
	v_mov_b32_e32 v58, v2
	v_mov_b32_e32 v59, v2
	v_mov_b32_e32 v60, v2
	v_mov_b32_e32 v61, v2
	v_mov_b32_e32 v62, v2
	v_mov_b32_e32 v63, v2
	v_mov_b32_e32 v64, v2
	v_mov_b32_e32 v65, v2
	v_mov_b32_e32 v66, v2
	v_mov_b32_e32 v67, v2
	v_mov_b32_e32 v68, v2
	v_mov_b32_e32 v69, v2
	v_mov_b32_e32 v70, v2
	v_mov_b32_e32 v71, v2
	v_mov_b32_e32 v72, v2
	v_mov_b32_e32 v73, v2
	v_mov_b32_e32 v74, v2
	v_mov_b32_e32 v75, v2
	v_mov_b32_e32 v76, v2
	v_mov_b32_e32 v77, v2
	v_mov_b32_e32 v78, v2
	v_mov_b32_e32 v79, v2
	v_mov_b32_e32 v80, v2
	v_mov_b32_e32 v81, v2
	v_mov_b32_e32 v90, v2
	v_mov_b32_e32 v91, v2
	v_mov_b32_e32 v92, v2
	v_mov_b32_e32 v93, v2
	v_mov_b32_e32 v94, v2
	v_mov_b32_e32 v95, v2
	v_mov_b32_e32 v96, v2
	v_mov_b32_e32 v97, v2
	v_mov_b32_e32 v106, v2
	v_mov_b32_e32 v107, v2
	v_mov_b32_e32 v108, v2
	v_mov_b32_e32 v109, v2
	v_mov_b32_e32 v110, v2
	v_mov_b32_e32 v111, v2
	v_mov_b32_e32 v112, v2
	v_mov_b32_e32 v113, v2
	v_mov_b32_e32 v82, v2
	v_mov_b32_e32 v83, v2
	v_mov_b32_e32 v84, v2
	v_mov_b32_e32 v85, v2
	v_mov_b32_e32 v86, v2
	v_mov_b32_e32 v87, v2
	v_mov_b32_e32 v88, v2
	v_mov_b32_e32 v89, v2
	v_mov_b32_e32 v98, v2
	v_mov_b32_e32 v99, v2
	v_mov_b32_e32 v100, v2
	v_mov_b32_e32 v101, v2
	v_mov_b32_e32 v102, v2
	v_mov_b32_e32 v103, v2
	v_mov_b32_e32 v104, v2
	v_mov_b32_e32 v105, v2
	v_mov_b32_e32 v114, v2
	v_mov_b32_e32 v115, v2
	v_mov_b32_e32 v116, v2
	v_mov_b32_e32 v117, v2
	v_mov_b32_e32 v118, v2
	v_mov_b32_e32 v119, v2
	v_mov_b32_e32 v120, v2
	v_mov_b32_e32 v121, v2
	v_mov_b32_e32 v122, v2
	v_mov_b32_e32 v123, v2
	v_mov_b32_e32 v124, v2
	v_mov_b32_e32 v125, v2
	v_mov_b32_e32 v126, v2
	v_mov_b32_e32 v127, v2
	v_mov_b32_e32 v128, v2
	v_mov_b32_e32 v129, v2
	.p2align	6
